# static s_setprio 1 for waves 0-3 raised from the MoBA gate phase (P3) through P5 instead of from P4
# speedup vs baseline: 1.0009x; 1.0009x over previous
.LBB0_510:
	s_cmp_lt_u32 s73, 4
	s_cbranch_scc0 .Lmy_prio_a
	s_setprio 1
.Lmy_prio_a:
	s_cmp_lt_i32 s74, 4
	s_cselect_b64 s[4:5], -1, 0
	s_and_b64 s[8:9], s[4:5], s[0:1]
	s_andn2_b64 vcc, exec, s[8:9]
	s_cbranch_vccnz .LBB0_717
	s_add_i32 s0, 0, 0x250a8
	v_mov_b32_e32 v0, s0
	ds_read_b64 v[0:1], v0
	s_mov_b32 s11, 0
	s_cmpk_lt_i32 s2, 0x400
	s_waitcnt lgkmcnt(0)
	v_readfirstlane_b32 s24, v1
	v_readfirstlane_b32 s25, v0
	s_cbranch_scc0 .LBB0_717
	v_mbcnt_lo_u32_b32 v0, -1, 0
	s_lshl_b32 s6, s73, 5
	v_mbcnt_hi_u32_b32 v84, -1, v0
	s_add_u32 s26, s25, 0x6600000
	v_lshrrev_b32_e32 v2, 5, v84
	v_and_b32_e32 v3, 64, v84
	s_addc_u32 s27, s24, 0
	v_lshlrev_b32_e32 v0, 3, v2
	v_lshlrev_b32_e32 v4, 4, v2
	v_lshlrev_b32_e32 v87, 2, v2
	v_xor_b32_e32 v2, 32, v84
	v_add_u32_e32 v3, 64, v3
	s_add_u32 s12, s25, 0xf000000
	v_cmp_lt_i32_e32 vcc, v2, v3
	s_addc_u32 s13, s24, 0
	s_add_u32 s33, s25, 0x3b800000
	v_cndmask_b32_e32 v2, v84, v2, vcc
	v_lshlrev_b32_e32 v89, 2, v2
	v_lshlrev_b64 v[2:3], v84, -1
	s_addc_u32 s50, s24, 0
	s_and_b32 s10, s78, 0xffffffc0
	v_not_b32_e32 v67, v3
	v_add_u32_e32 v3, s10, v84
	v_not_b32_e32 v66, v2
	v_lshlrev_b32_e32 v2, 2, v84
	v_lshlrev_b32_e32 v68, 1, v3
	v_ashrrev_i32_e32 v5, 6, v3
	v_add_u32_e32 v6, 0x200, v3
	v_add_u32_e32 v7, 0x400, v3
	v_add_u32_e32 v8, 0x600, v3
	v_add_u32_e32 v9, 0x800, v3
	v_add_u32_e32 v10, 0xa00, v3
	v_add_u32_e32 v11, 0xc00, v3
	v_add_u32_e32 v3, 0xe00, v3
	v_and_b32_e32 v1, 31, v84
	s_movk_i32 s7, 0x110
	v_and_b32_e32 v2, 0xfc, v2
	v_ashrrev_i32_e32 v6, 6, v6
	v_ashrrev_i32_e32 v7, 6, v7
	v_ashrrev_i32_e32 v8, 6, v8
	v_ashrrev_i32_e32 v9, 6, v9
	v_ashrrev_i32_e32 v10, 6, v10
	v_ashrrev_i32_e32 v11, 6, v11
	v_ashrrev_i32_e32 v3, 6, v3
	v_add_u32_e32 v85, 0, v84
	v_or_b32_e32 v86, s6, v1
	v_mad_u32_u24 v1, v1, s7, 0
	v_add_u32_e32 v2, 0, v2
	v_add_u32_e32 v70, 0x400, v68
	v_add_u32_e32 v72, 0x800, v68
	v_add_u32_e32 v74, 0xc00, v68
	v_add_u32_e32 v76, 0x1000, v68
	v_add_u32_e32 v78, 0x1400, v68
	v_add_u32_e32 v80, 0x1800, v68
	v_add_u32_e32 v82, 0x1c00, v68
	v_mul_lo_u32 v5, v5, s7
	v_mul_lo_u32 v6, v6, s7
	v_mul_lo_u32 v7, v7, s7
	v_mul_lo_u32 v8, v8, s7
	v_mul_lo_u32 v9, v9, s7
	v_mul_lo_u32 v10, v10, s7
	v_mul_lo_u32 v11, v11, s7
	v_mul_lo_u32 v3, v3, s7
	v_mov_b32_e32 v65, 0
	v_or_b32_e32 v88, 32, v87
	v_cmp_gt_u32_e64 s[0:1], 32, v84
	v_cmp_eq_u32_e64 s[4:5], 0, v84
	v_ashrrev_i32_e32 v69, 31, v68
	v_ashrrev_i32_e32 v71, 31, v70
	v_ashrrev_i32_e32 v73, 31, v72
	v_ashrrev_i32_e32 v75, 31, v74
	v_ashrrev_i32_e32 v77, 31, v76
	v_ashrrev_i32_e32 v79, 31, v78
	v_ashrrev_i32_e32 v81, 31, v80
	v_ashrrev_i32_e32 v83, 31, v82
	v_or_b32_e32 v90, 1, v87
	v_or_b32_e32 v91, 2, v87
	v_or_b32_e32 v92, 3, v87
	v_add_u32_e32 v93, 8, v87
	v_add_u32_e32 v94, 9, v87
	v_add_u32_e32 v95, 10, v87
	v_add_u32_e32 v96, 11, v87
	v_or_b32_e32 v97, 16, v87
	v_or_b32_e32 v98, 17, v87
	v_or_b32_e32 v99, 18, v87
	v_or_b32_e32 v100, 19, v87
	v_add_u32_e32 v101, 24, v87
	v_add_u32_e32 v102, 25, v87
	v_add_u32_e32 v103, 26, v87
	v_add_u32_e32 v104, 27, v87
	v_or_b32_e32 v105, 33, v87
	v_or_b32_e32 v106, 34, v87
	v_or_b32_e32 v107, 35, v87
	v_add_u32_e32 v108, 40, v87
	v_add_u32_e32 v109, 41, v87
	v_add_u32_e32 v110, 42, v87
	v_add_u32_e32 v111, 43, v87
	v_or_b32_e32 v112, 48, v87
	v_or_b32_e32 v113, 49, v87
	v_or_b32_e32 v114, 50, v87
	v_or_b32_e32 v115, 51, v87
	v_add_u32_e32 v116, 56, v87
	v_add_u32_e32 v117, 57, v87
	v_add_u32_e32 v118, 58, v87
	v_add_u32_e32 v119, 59, v87
	v_add_u32_e32 v120, v2, v5
	v_add_u32_e32 v121, v2, v6
	v_add_u32_e32 v122, v2, v7
	v_add_u32_e32 v123, v2, v8
	v_add_u32_e32 v124, v2, v9
	v_add_u32_e32 v125, v2, v10
	v_add_u32_e32 v126, v2, v11
	v_add_u32_e32 v127, v2, v3
	v_lshlrev_b32_e32 v64, 1, v0
	v_add_u32_e32 v128, s6, v85
	v_add_u32_e32 v129, v1, v4
	s_mov_b32 s51, s2
	s_branch .LBB0_515
